# attention: one static s_setprio 1 for waves 4-7 for the whole phase (strategy: static priority for the younger half)
# baseline (speedup 1.0000x reference)
; __device__ __forceinline__ int tid_opaque(int wv) { return wv * 64 + lane_fresh(); }
; __device__ __forceinline__ void attn_mfma(PP p, unsigned char* shm, int wv) {
;     const int tid = tid_opaque(wv);
;     const int lane = tid & 63, wave = wv, l31 = lane & 31, hl = lane >> 5;
;     const bf16_t* proj = (const bf16_t*)(p->ws + WS_PROJ);
;     bf16_t* att = (bf16_t*)(p->ws + WS_ATT);
;     const float L2E = 1.4426950408889634f;
;     const float SC2 = 0.125f * L2E;
;     for (int item = blockIdx.x; item < 512; item += gridDim.x) {
;         const int hk = item & 1, qb = (item >> 1) & 127, b = item >> 8;
;         const int g = wave >> 1, qh = wave & 1, hq = hk * 4 + g;
;         const int qrow0 = b * S + 128 * qb + 64 * qh;
.LBB0_453:
	s_cmpk_lt_i32 s2, 0x200
	s_mov_b64 s[4:5], s[0:1]
	s_cselect_b64 s[22:23], -1, 0
	s_cmpk_gt_i32 s2, 0x1ff
	s_cbranch_scc1 .LBB0_489
	s_cmpk_lt_u32 s33, 0x100
	s_cbranch_scc1 .Lsp_attn
	s_setprio 1
.Lsp_attn:
	s_load_dwordx2 s[14:15], s[4:5], 0xd0
	s_load_dwordx2 s[8:9], s[4:5], 0x78
	v_mbcnt_lo_u32_b32 v1, s27, 0
	v_mbcnt_hi_u32_b32 v1, s27, v1
	v_mov_b32_e32 v0, 0
	s_waitcnt lgkmcnt(0)
	s_add_u32 s4, s14, 0x9c77000
	v_bfe_u32 v6, v1, 5, 1
	v_and_b32_e32 v8, 31, v1
	s_addc_u32 s5, s15, 0
	v_add_u32_e32 v5, s33, v1
	s_bfe_u32 s6, s56, 0x10006
	v_lshlrev_b32_e32 v2, 3, v6
	v_mov_b32_e32 v3, v0
	v_lshlrev_b32_e32 v1, 3, v1
	s_lshr_b32 s27, s56, 7
	s_lshl_b32 s16, s6, 6
	v_cmp_eq_u32_e32 vcc, 0, v6
	v_and_b32_e32 v162, 56, v1
	v_lshlrev_b32_e32 v9, 4, v6
	v_lshlrev_b32_e32 v181, 2, v6
	v_lshl_add_u64 v[6:7], s[14:15], 0, v[2:3]
	s_mov_b64 s[14:15], 0x1c77000
	v_lshlrev_b32_e32 v4, 1, v162
	s_bitcmp1_b32 s56, 6
	v_lshl_add_u64 v[164:165], v[6:7], 0, s[14:15]
	v_ashrrev_i32_e32 v182, 3, v5
	v_add_u32_e32 v3, 0x200, v5
	v_mul_u32_u24_e32 v7, 0x108, v8
	v_mov_b32_e32 v5, v0
	v_add_u32_e32 v1, 0, v4
	s_cselect_b64 s[10:11], -1, 0
	s_cmp_eq_u32 s6, 0
	v_ashrrev_i32_e32 v183, 3, v3
	s_movk_i32 s6, 0x90
	v_lshl_add_u64 v[166:167], s[4:5], 0, v[4:5]
	v_add3_u32 v4, v7, v2, 0
	v_mul_lo_u32 v184, v182, s6
	v_mul_lo_u32 v186, v183, s6
	v_add_u32_e32 v187, 0x4800, v4
	v_mul_u32_u24_e32 v4, 0x90, v8
	v_lshl_add_u32 v3, v182, 1, 0
	v_mul_u32_u24_e32 v185, 0x108, v162
	v_lshl_add_u32 v6, v183, 1, 0
	v_add3_u32 v188, v4, v9, 0
	v_sub_u32_e32 v4, v181, v8
	v_add_u32_e32 v190, v1, v184
	v_add_u32_e32 v192, v1, v186
	v_mbcnt_lo_u32_b32 v1, -1, 0
	s_mov_b32 s7, 0
	v_cndmask_b32_e64 v163, 0, 1.0, vcc
	s_cselect_b64 s[12:13], -1, 0
	v_or_b32_e32 v180, s16, v8
	v_subrev_u32_e32 v189, s16, v4
	s_movk_i32 s30, 0xe00
	v_mov_b64_e32 v[168:169], s[4:5]
	v_lshlrev_b32_e32 v170, 1, v2
	v_mov_b32_e32 v171, v0
	v_lshlrev_b32_e32 v172, 1, v162
	v_mov_b32_e32 v173, v0
	v_add_u32_e32 v191, v3, v185
	v_add_u32_e32 v193, v6, v185
	s_mov_b32 s31, 0x3e38aa3b
	v_mov_b32_e32 v194, 0xf149f2ca
	v_mbcnt_hi_u32_b32 v195, -1, v1
	s_mov_b32 s34, s2
	s_branch .LBB0_456

; __device__ __forceinline__ int tid_opaque(int wv) { return wv * 64 + lane_fresh(); }
; __device__ __forceinline__ void xcd_barrier(const XcdBarrier& b, int wv) {
;     asm volatile("s_waitcnt vmcnt(0)" ::: "memory");
;     __syncthreads();
;     if (tid_opaque(wv) == 0) {
;         unsigned* bar = b.bar;
;         __builtin_amdgcn_s_waitcnt(0);
;         unsigned nloc = b.st[0], nx = b.st[1];
;         if (nloc == 0u) { xcd_barrier_complete(bar, b.x, nloc, nx); b.st[0] = nloc; b.st[1] = nx; }
; __device__ __forceinline__ void attn_mfma(PP p, unsigned char* shm, int wv) {
;     ...
;     __syncthreads();
.LBB0_489:
	s_setprio 0
	s_mov_b64 s[6:7], s[0:1]
	s_mov_b32 s4, -1
	s_barrier
	s_getreg_b32 s8, hwreg(HW_REG_XCC_ID, 0, 4)
	s_waitcnt vmcnt(0)
	s_barrier
	s_nop 0
	v_mbcnt_lo_u32_b32 v0, s4, 0
	v_mbcnt_hi_u32_b32 v0, s4, v0
	v_cmp_eq_u32_e32 vcc, s3, v0
	s_and_saveexec_b64 s[4:5], vcc
	s_cbranch_execz .LBB0_541
	s_add_i32 s9, 0, 0x22000
	v_mov_b32_e32 v0, s9
	s_load_dwordx2 s[6:7], s[6:7], 0xd0
	s_waitcnt vmcnt(0) expcnt(0) lgkmcnt(0)
	ds_read_b32 v2, v0
	s_add_i32 s9, 0, 0x22004
	v_mov_b32_e32 v0, s9
	ds_read_b32 v0, v0
	s_and_b32 s27, s8, 15
	s_waitcnt lgkmcnt(1)
	v_cmp_ne_u32_e32 vcc, 0, v2
	s_cbranch_vccnz .LBB0_505
	s_add_u32 s8, s6, 0x1c73200
	s_addc_u32 s9, s7, 0
	s_add_u32 s10, s6, 0x1c73400
	s_addc_u32 s11, s7, 0
	s_add_u32 s12, s6, 0x1c73500
	s_addc_u32 s13, s7, 0
	s_add_u32 s14, s6, 0x1c73600
	s_addc_u32 s15, s7, 0
	s_add_u32 s16, s6, 0x1c73700
	s_addc_u32 s17, s7, 0
	s_add_u32 s18, s6, 0x1c73800
	s_addc_u32 s19, s7, 0
	s_add_u32 s20, s6, 0x1c73900
	s_addc_u32 s21, s7, 0
	s_add_u32 s28, s6, 0x1c73a00
	s_addc_u32 s29, s7, 0
	s_add_u32 s30, s6, 0x1c73b00
	s_addc_u32 s31, s7, 0
	s_add_u32 s34, s6, 0x1c73c00
	s_addc_u32 s35, s7, 0
	s_add_u32 s36, s6, 0x1c73d00
	s_addc_u32 s37, s7, 0
	s_add_u32 s38, s6, 0x1c73e00
	s_addc_u32 s39, s7, 0
	s_add_u32 s40, s6, 0x1c73f00
	s_addc_u32 s41, s7, 0
	s_add_u32 s42, s6, 0x1c74000
	s_addc_u32 s43, s7, 0
	s_add_u32 s44, s6, 0x1c74100
	s_addc_u32 s45, s7, 0
	s_add_u32 s46, s6, 0x1c74200
	s_addc_u32 s47, s7, 0
	s_mul_i32 s56, s25, s62
	s_add_u32 s48, s6, 0x1c74300
	s_mul_i32 s56, s56, s24
	s_addc_u32 s49, s7, 0
	s_mov_b32 s57, 1
	v_mov_b32_e32 v16, 0
	s_branch .LBB0_493
